# DIL unit: bias-row load no longer waited before K-image DMA issue (LDS write deferred to the unit's first full wait)
# speedup vs baseline: 1.0118x; 1.0007x over previous
; __global__ void __launch_bounds__(NWAVES * 64, 2) mk_fwd(Args a) {
;     ...
;             for (int u = vcu; u < 512; u += G) { const int x = u & 15, bh = u >> 4, h = bh & 7;
;                 int tu = tid; asm volatile("" : "+v"(tu));
;                 if (tu < 192) { const int jk = tu - 32; btab[tu] = (jk >= 0 && jk <= 128) ? biasrel[(gi * 8 + h) * 129 + jk] : -1e30f; }
.LBB0_658:
	v_mov_b32_e32 v237, v211
	s_movk_i32 s0, 0xc0
	s_bfe_u32 s21, s19, 0x30004
	s_nop 0
	v_cmp_gt_i32_e32 vcc, s0, v237
	s_and_saveexec_b64 s[0:1], vcc
	s_cbranch_execz .LBB0_662
	s_waitcnt lgkmcnt(0)
	v_subrev_u32_e32 v1, 32, v237
	s_movk_i32 s2, 0x81
	v_cmp_gt_u32_e32 vcc, s2, v1
	v_mov_b32_e32 v108, 0xf149f2ca
	s_and_saveexec_b64 s[2:3], vcc
	s_cbranch_execz .LBB0_661
	s_or_b32 s20, s21, s13
	s_mulk_i32 s20, 0x81
	v_add_u32_e32 v0, s20, v1
	v_ashrrev_i32_e32 v1, 31, v0
	v_lshl_add_u64 v[0:1], v[0:1], 2, s[4:5]
	global_load_dword v108, v[0:1], off
.LBB0_661:
	s_or_b64 exec, exec, s[2:3]
	v_lshl_add_u32 v109, v237, 2, 0
	v_add_u32_e32 v109, 0x20000, v109

; #define LAS __attribute__((address_space(3)))
; __device__ __forceinline__ void glds16(const void* gsrc, LAS unsigned char* dst_uniform) { __builtin_amdgcn_global_load_lds((const unsigned*)gsrc, (LAS unsigned*)dst_uniform, 16, 0, 0); }
; #define ATT_SYNC() do { asm volatile("s_waitcnt vmcnt(0) lgkmcnt(0)" ::: "memory"); __syncthreads(); } while (0)
; __device__ __forceinline__ void dil_unit(LAS unsigned char* lds, const LAS float* btab, const bf16_t* QKV, int gi, int ldil, int b, int h, int r, int ub, bf16_t* AO, float* lseacc, const int tid) {
;     ...
; #pragma unroll 4
;     for (int ii = 0; ii < 12; ++ii) { const int i = wid * 12 + ii, kk = 4 * i + (lane >> 4), c = (lane & 15) ^ (kk & 15); int ki = k0 + kk; ki = ki < 0 ? 0 : (ki >= sub_len ? sub_len - 1 : ki);
;         glds16(base + (tokb + ((size_t)ki << ldil)) * 3072 + 1024 + c * 8, lds + i * 1024); }
;     const int qi = ub * 256 + wid * 32 + r32; const size_t qtok = tokb + ((size_t)qi << ldil);
;     bf16x8 qf[8]; { const bf16_t* qp = base + qtok * 3072 + hi * 8;
; #pragma unroll
;         for (int s = 0; s < 8; ++s) qf[s] = *(const bf16x8*)(qp + 16 * s); }
;     ATT_SYNC();
;     f32x16 S[5];
;     int r15 = r32 & 15; asm volatile("" : "+v"(r15));
; #pragma unroll
;     for (int t = 0; t < 5; ++t) { f32x16 acc = {}; const lds_cptr kp = (lds_cptr)lds + (32 * wid + 32 * t + r32) * 256;
; #pragma unroll
;         for (int s = 0; s < 8; ++s) { const bf16x8 kf = *(const LAS bf16x8*)(kp + (((2 * s + hi) ^ r15) << 4)); acc = __builtin_amdgcn_mfma_f32_32x32x16_bf16(kf, qf[s], acc, 0, 0, 0); }
; __global__ void __launch_bounds__(NWAVES * 64, 2) mk_fwd(Args a) {
;     ...
;                 if (tu < 192) { const int jk = tu - 32; btab[tu] = (jk >= 0 && jk <= 128) ? biasrel[(gi * 8 + h) * 129 + jk] : -1e30f; }
.LBB0_663:
	v_add_u32_e32 v10, s25, v2
	v_subrev_u32_e32 v0, 64, v10
	s_waitcnt lgkmcnt(0)
	v_min_i32_e32 v1, s18, v0
	v_cmp_lt_i32_e32 vcc, -1, v0
	v_add_u32_e32 v8, s25, v3
	v_xor_b32_e32 v9, v8, v237
	v_cndmask_b32_e32 v0, 0, v1, vcc
	v_ashrrev_i32_e32 v1, 31, v0
	v_lshlrev_b64 v[0:1], s12, v[0:1]
	v_lshl_add_u64 v[4:5], v[0:1], 0, s[0:1]
	v_mov_b64_e32 v[0:1], s[2:3]
	v_mad_u64_u32 v[6:7], s[30:31], v4, s36, v[0:1]
	v_mov_b32_e32 v4, v7
	v_mad_u64_u32 v[4:5], s[30:31], v5, s36, v[4:5]
	v_mov_b32_e32 v7, v4
	v_lshlrev_b32_e32 v4, 4, v9
	v_and_b32_e32 v208, 0xf0, v4
	v_lshl_add_u64 v[4:5], v[6:7], 0, v[208:209]
	v_lshl_add_u64 v[4:5], v[4:5], 0, s[38:39]
	s_mov_b32 m0, s28
	s_add_i32 s25, s25, 16
	global_load_lds_dwordx4 v[4:5], off
	v_add_u32_e32 v4, 4, v8
	v_xor_b32_e32 v9, v4, v237
	v_subrev_u32_e32 v4, 60, v10
	v_min_i32_e32 v5, s18, v4
	v_cmp_lt_i32_e32 vcc, -1, v4
	s_add_i32 m0, s28, 0x400
	s_nop 0
	v_cndmask_b32_e32 v4, 0, v5, vcc
	v_ashrrev_i32_e32 v5, 31, v4
	v_lshlrev_b64 v[4:5], s12, v[4:5]
	v_lshl_add_u64 v[4:5], v[4:5], 0, s[0:1]
	v_mad_u64_u32 v[6:7], s[30:31], v4, s36, v[0:1]
	v_mov_b32_e32 v4, v7
	v_mad_u64_u32 v[4:5], s[30:31], v5, s36, v[4:5]
	v_mov_b32_e32 v7, v4
	v_lshlrev_b32_e32 v4, 4, v9
	v_and_b32_e32 v208, 0xf0, v4
	v_lshl_add_u64 v[4:5], v[6:7], 0, v[208:209]
	v_lshl_add_u64 v[4:5], v[4:5], 0, s[38:39]
	global_load_lds_dwordx4 v[4:5], off
	v_add_u32_e32 v4, 8, v8
	v_xor_b32_e32 v9, v4, v237
	v_subrev_u32_e32 v4, 56, v10
	v_min_i32_e32 v5, s18, v4
	v_cmp_lt_i32_e32 vcc, -1, v4
	s_add_i32 m0, s28, 0x800
	s_nop 0
	v_cndmask_b32_e32 v4, 0, v5, vcc
	v_ashrrev_i32_e32 v5, 31, v4
	v_lshlrev_b64 v[4:5], s12, v[4:5]
	v_lshl_add_u64 v[4:5], v[4:5], 0, s[0:1]
	v_mad_u64_u32 v[6:7], s[30:31], v4, s36, v[0:1]
	v_mov_b32_e32 v4, v7
	v_mad_u64_u32 v[4:5], s[30:31], v5, s36, v[4:5]
	v_mov_b32_e32 v7, v4
	v_lshlrev_b32_e32 v4, 4, v9
	v_and_b32_e32 v208, 0xf0, v4
	v_lshl_add_u64 v[4:5], v[6:7], 0, v[208:209]
	v_lshl_add_u64 v[4:5], v[4:5], 0, s[38:39]
	global_load_lds_dwordx4 v[4:5], off
	v_add_u32_e32 v4, 12, v8
	v_xor_b32_e32 v6, v4, v237
	v_subrev_u32_e32 v4, 52, v10
	v_min_i32_e32 v5, s18, v4
	v_cmp_lt_i32_e32 vcc, -1, v4
	s_add_i32 m0, s28, 0xc00
	s_addk_i32 s28, 0x1000
	v_cndmask_b32_e32 v4, 0, v5, vcc
	v_ashrrev_i32_e32 v5, 31, v4
	v_lshlrev_b64 v[4:5], s12, v[4:5]
	v_lshl_add_u64 v[4:5], v[4:5], 0, s[0:1]
	v_mad_u64_u32 v[0:1], s[30:31], v4, s36, v[0:1]
	v_mov_b32_e32 v4, v1
	v_mad_u64_u32 v[4:5], s[30:31], v5, s36, v[4:5]
	v_mov_b32_e32 v1, v4
	v_lshlrev_b32_e32 v4, 4, v6
	v_and_b32_e32 v208, 0xf0, v4
	v_lshl_add_u64 v[0:1], v[0:1], 0, v[208:209]
	v_lshl_add_u64 v[0:1], v[0:1], 0, s[38:39]
	global_load_lds_dwordx4 v[0:1], off
	s_cmp_eq_u32 s25, 48
	s_cbranch_scc0 .LBB0_663
	s_lshl_b32 s28, s20, 5
	v_and_b32_e32 v240, 31, v237
	s_add_i32 s25, s28, s27
	v_or_b32_e32 v0, s25, v240
	v_ashrrev_i32_e32 v1, 31, v0
	v_lshlrev_b64 v[0:1], s12, v[0:1]
	v_lshl_add_u64 v[218:219], v[0:1], 0, s[0:1]
	v_mov_b64_e32 v[0:1], s[2:3]
	v_mad_u64_u32 v[0:1], s[30:31], v218, s36, v[0:1]
	v_mov_b32_e32 v2, v1
	v_lshrrev_b32_e32 v239, 5, v238
	v_mad_u64_u32 v[2:3], s[30:31], v219, s36, v[2:3]
	v_mov_b32_e32 v1, v2
	v_lshlrev_b32_e32 v220, 4, v239
	v_mov_b32_e32 v221, v209
	v_lshl_add_u64 v[4:5], v[0:1], 0, v[220:221]
	global_load_dwordx4 v[0:3], v[4:5], off
	global_load_dwordx4 v[80:83], v[4:5], off offset:32
	global_load_dwordx4 v[84:87], v[4:5], off offset:64
	global_load_dwordx4 v[88:91], v[4:5], off offset:96
	global_load_dwordx4 v[92:95], v[4:5], off offset:128
	global_load_dwordx4 v[96:99], v[4:5], off offset:160
	global_load_dwordx4 v[100:103], v[4:5], off offset:192
	global_load_dwordx4 v[104:107], v[4:5], off offset:224
	s_lshl_b32 s29, s20, 13
	v_and_b32_e32 v4, 15, v237
	s_add_i32 s29, s29, 0
	v_cmp_gt_i32_e32 vcc, 0xc0, v237
	s_nop 1
	s_and_saveexec_b64 vcc, vcc
	s_waitcnt vmcnt(0)
	ds_write_b32 v109, v108
	s_mov_b64 exec, vcc
	s_waitcnt vmcnt(0) lgkmcnt(0)
	s_waitcnt vmcnt(0) lgkmcnt(0)
	s_barrier
	v_lshl_add_u32 v6, v240, 8, s29
	v_xor_b32_e32 v5, v4, v239
	v_lshl_add_u32 v52, v5, 4, v6
	v_bitop3_b32 v5, v4, v239, 2 bitop3:0x1e
	v_lshl_add_u32 v53, v5, 4, v6
	v_bitop3_b32 v5, v4, v239, 4 bitop3:0x1e
	v_lshl_add_u32 v56, v5, 4, v6
	v_bitop3_b32 v5, v4, v239, 6 bitop3:0x1e
	v_lshl_add_u32 v57, v5, 4, v6
	v_bitop3_b32 v5, v4, v239, 8 bitop3:0x1e
	v_lshl_add_u32 v60, v5, 4, v6
	v_bitop3_b32 v5, v4, v239, 10 bitop3:0x1e
	v_lshl_add_u32 v61, v5, 4, v6
	v_bitop3_b32 v5, v4, v239, 12 bitop3:0x1e
	v_bitop3_b32 v4, v4, v239, 14 bitop3:0x1e
	v_lshl_add_u32 v65, v5, 4, v6
	v_lshl_add_u32 v66, v4, 4, v6
	ds_read_b128 v[24:27], v53
	ds_read_b128 v[4:7], v53 offset:8192
	ds_read_b128 v[32:35], v57
	ds_read_b128 v[8:11], v57 offset:8192
	ds_read_b128 v[36:39], v61
	ds_read_b128 v[12:15], v61 offset:8192
	ds_read_b128 v[40:43], v66
	ds_read_b128 v[16:19], v66 offset:8192
	ds_read_b128 v[44:47], v52 offset:8192
	ds_read_b128 v[20:23], v52 offset:16384
	ds_read_b128 v[128:131], v56 offset:8192
	ds_read_b128 v[28:31], v56 offset:16384
	ds_read_b128 v[136:139], v60 offset:8192
	ds_read_b128 v[108:111], v60 offset:16384
	ds_read_b128 v[144:147], v65 offset:8192
	ds_read_b128 v[112:115], v65 offset:16384
	ds_read_b128 v[148:151], v53 offset:16384
	ds_read_b128 v[116:119], v53 offset:24576
	ds_read_b128 v[160:163], v57 offset:16384
	ds_read_b128 v[120:123], v57 offset:24576
	ds_read_b128 v[168:171], v61 offset:16384
	ds_read_b128 v[124:127], v61 offset:24576
	ds_read_b128 v[176:179], v66 offset:16384
	ds_read_b128 v[132:135], v66 offset:24576
	ds_read_b128 v[48:51], v52
	ds_read_b128 v[140:143], v52 offset:32768
	ds_read_b128 v[192:195], v52 offset:24576
	ds_read_b128 v[152:155], v53 offset:32768
	ds_read_b128 v[52:55], v56
	ds_read_b128 v[156:159], v56 offset:32768
	ds_read_b128 v[196:199], v56 offset:24576
	ds_read_b128 v[164:167], v57 offset:32768
	ds_read_b128 v[56:59], v60
	ds_read_b128 v[172:175], v60 offset:32768
	ds_read_b128 v[200:203], v60 offset:24576
	ds_read_b128 v[180:183], v61 offset:32768
	ds_read_b128 v[60:63], v65
	ds_read_b128 v[184:187], v65 offset:32768
	ds_read_b128 v[204:207], v65 offset:24576
	ds_read_b128 v[188:191], v66 offset:32768
	s_sub_i32 s27, s27, 64
	v_lshlrev_b32_e32 v64, 3, v239
	s_waitcnt vmcnt(0) lgkmcnt(0)
	v_bfe_u32 v65, v237, 2, 3
	v_or3_b32 v64, v65, s27, v64
	v_lshlrev_b32_e32 v65, 3, v237
	v_lshrrev_b32_e32 v221, 2, v237
	v_and_b32_e32 v212, 24, v65
	s_mov_b32 s29, 0
	s_waitcnt lgkmcnt(0)
	s_barrier
